# DA: stage next K/V tile into LDS and issue following tile loads mid-body (per-wave flag), loop top reduced to wait+barrier
# speedup vs baseline: 1.0554x; 1.0054x over previous
; __device__ __forceinline__ int opaque_tid(int wv) { unsigned ones = ~0u; asm volatile("" : "+s"(ones)); int lane = __builtin_amdgcn_mbcnt_hi(ones, __builtin_amdgcn_mbcnt_lo(ones, 0u)); int t = (wv << 6) | lane; asm volatile("" : "+v"(t)); return t; }
; template <int NC, int DQK, int DV, bool CAUSAL, bool PF> ...
;     ...
;   int tid = opaque_tid(wv), wid = tid >> 6, lane = tid & 63, fr = lane & 15, fq = lane >> 4;
;   int qw0 = q0 + wid * 16, qpos = qw0 + fr;
;   bf16x8 qf[NC][NKS];
;   _Pragma("unroll") for (int c = 0; c < NC; ++c) _Pragma("unroll") for (int ks = 0; ks < NKS; ++ks)
;     qf[c][ks] = *(const bf16x8*)&Qg[(long)(wid * 16 + fr) * q_stride + c * DQK + ks * 32 + fq * 8];
;   f32x4 O[NC][NVT];
;   _Pragma("unroll") for (int c = 0; c < NC; ++c) _Pragma("unroll") for (int v = 0; v < NVT; ++v) O[c][v] = f32x4{0.f, 0.f, 0.f, 0.f};
;   float mrun[NC], lsum[NC];
;   _Pragma("unroll") for (int c = 0; c < NC; ++c) { mrun[c] = -1e30f; lsum[c] = 0.f; }
;   const __amdgpu_buffer_rsrc_t rsK = __builtin_amdgcn_make_buffer_rsrc((void*)Kg, 0, 0x7fffffff, 0x00020000);
;   const __amdgpu_buffer_rsrc_t rsV = __builtin_amdgcn_make_buffer_rsrc((void*)VTg, 0, 0x7fffffff, 0x00020000);
;   const __amdgpu_buffer_rsrc_t rsNK = __builtin_amdgcn_make_buffer_rsrc((void*)nKg, 0, 0x7fffffff, 0x00020000);
;   const __amdgpu_buffer_rsrc_t rsNV = __builtin_amdgcn_make_buffer_rsrc((void*)nVTg, 0, 0x7fffffff, 0x00020000);
;   int kvo[KPT], vvo[VPT];
;   _Pragma("unroll") for (int i = 0; i < KPT; ++i) { int id = tid + i * 512, row = id / KCH, cc = id % KCH; kvo[i] = (row * k_stride + cc * 8) * 2; }
;   _Pragma("unroll") for (int i = 0; i < VPT; ++i) { int id = tid + i * 512, row = id >> 3, cc = id & 7; vvo[i] = (row * vt_stride + cc * 8) * 2; }
.LBB0_1782:
	s_lshl_b64 s[18:19], s[0:1], 10
	v_and_b32_e32 v6, 63, v0
	v_and_b32_e32 v196, 15, v0
	v_bfe_u32 v7, v0, 4, 2
	v_and_b32_e32 v206, 32, v5
	v_lshlrev_b32_e32 v5, 4, v0
	v_lshlrev_b32_e32 v8, 1, v0
	v_lshrrev_b32_e32 v0, 3, v0
	s_movk_i32 s0, 0xa0
	v_mul_lo_u32 v208, v0, s0
	v_lshrrev_b32_e32 v0, 3, v3
	v_and_b32_e32 v1, -16, v1
	v_mul_lo_u32 v207, v0, s0
	s_sub_i32 s0, s8, 51
	v_mov_b32_e32 v52, v33
	v_mov_b32_e32 v53, v33
	s_lshr_b32 s30, s8, 6
	v_add_u32_e32 v197, s8, v1
	v_and_b32_e32 v5, 16, v5
	v_and_b32_e32 v8, 4, v8
	v_lshlrev_b32_e32 v6, 2, v6
	v_lshlrev_b32_e32 v190, 2, v7
	v_add3_u32 v0, s0, v1, v196
	v_mov_b32_e32 v50, v33
	v_mov_b32_e32 v51, v33
	v_mov_b64_e32 v[64:65], v[52:53]
	v_mov_b64_e32 v[80:81], v[52:53]
	v_mov_b64_e32 v[92:93], v[52:53]
	v_mov_b64_e32 v[100:101], v[52:53]
	v_mov_b64_e32 v[108:109], v[52:53]
	v_mov_b64_e32 v[56:57], v[52:53]
	v_mov_b64_e32 v[84:85], v[52:53]
	v_mov_b64_e32 v[112:113], v[52:53]
	v_mov_b64_e32 v[104:105], v[52:53]
	v_mov_b64_e32 v[96:97], v[52:53]
	v_mov_b64_e32 v[76:77], v[52:53]
	v_mov_b64_e32 v[72:73], v[52:53]
	v_mov_b64_e32 v[68:69], v[52:53]
	v_mov_b64_e32 v[60:61], v[52:53]
	v_mov_b64_e32 v[88:89], v[52:53]
	v_or_b32_e32 v203, 15, v197
	v_add_u32_e32 v202, 0xffffff8f, v197
	s_movk_i32 s31, 0x80
	v_xor_b32_e32 v189, 0x80, v6
	v_mul_lo_u32 v210, v2, s74
	v_mul_lo_u32 v209, v4, s74
	v_mul_u32_u24_e32 v195, 0x110, v196
	v_mul_u32_u24_e32 v193, 0xa0, v196
	s_add_i32 s30, s30, 1
	v_sub_u32_e32 v213, v0, v190
	s_mov_b32 s34, 0
	v_mov_b32_e32 v191, 0
	v_mov_b32_e32 v171, 0xf149f2ca
	s_mov_b32 s35, 63
	s_mov_b32 s36, 0x20000
	v_lshlrev_b32_e32 v211, 1, v5
	v_lshlrev_b32_e32 v212, 1, v8
	v_mov_b64_e32 v[62:63], v[50:51]
	v_mov_b64_e32 v[78:79], v[50:51]
	v_mov_b64_e32 v[90:91], v[50:51]
	v_mov_b64_e32 v[98:99], v[50:51]
	v_mov_b64_e32 v[106:107], v[50:51]
	v_mov_b32_e32 v194, 0xf149f2ca
	v_mov_b32_e32 v192, 0
	v_mov_b64_e32 v[54:55], v[50:51]
	v_mov_b64_e32 v[82:83], v[50:51]
	v_mov_b64_e32 v[110:111], v[50:51]
	v_mov_b64_e32 v[102:103], v[50:51]
	v_mov_b64_e32 v[94:95], v[50:51]
	v_mov_b64_e32 v[74:75], v[50:51]
	v_mov_b64_e32 v[70:71], v[50:51]
	v_mov_b64_e32 v[66:67], v[50:51]
	v_mov_b64_e32 v[58:59], v[50:51]
	v_mov_b64_e32 v[86:87], v[50:51]
	s_mov_b32 s9, 0
	s_branch .LBB0_1785

; #define FA_PREFETCH(kt_) do { int k0_ = (kt_) * 64; \
;     _Pragma("unroll") for (int i = 0; i < KPT; ++i) kreg[i] = __builtin_amdgcn_raw_buffer_load_b128(rsK, kvo[i], k0_ * k_stride * 2, 0); \
;     _Pragma("unroll") for (int i = 0; i < VPT; ++i) vreg[i] = __builtin_amdgcn_raw_buffer_load_b128(rsV, vvo[i], k0_ * 2, 0); } while (0)
; #define FA_PREFETCH_NEXT() do { \
;     _Pragma("unroll") for (int i = 0; i < KPT; ++i) kreg[i] = __builtin_amdgcn_raw_buffer_load_b128(rsNK, kvo[i], 0, 0); \
;     _Pragma("unroll") for (int i = 0; i < VPT; ++i) vreg[i] = __builtin_amdgcn_raw_buffer_load_b128(rsNV, vvo[i], 0, 0); } while (0)
; template <int NC, int DQK, int DV, bool CAUSAL, bool PF> ...
;     ...
;   for (int kt = 0; kt < nkt; ++kt) {
;     if (!PF) FA_PREFETCH(kt);
;     u16* Kb = Ks + (kt & 1) * KBUF; u16* Vb = Vs + (kt & 1) * VBUF;
;     _Pragma("unroll") for (int i = 0; i < KPT; ++i) { int id = tid + i * 512, row = id / KCH, cc = id % KCH; *(u32x4*)&Kb[row * KLD + cc * 8] = kreg[i]; }
;     _Pragma("unroll") for (int i = 0; i < VPT; ++i) {
;       int id = tid + i * 512, row = id >> 3, cc = id & 7;
;       int pos = 32 * (cc >> 2) + 16 * (cc & 1) + 4 * ((cc >> 1) & 1);
;       uint2 lo2, hi2; lo2.x = vreg[i][0]; lo2.y = vreg[i][1]; hi2.x = vreg[i][2]; hi2.y = vreg[i][3];
;       *(uint2*)&Vb[row * VLD + pos] = lo2; *(uint2*)&Vb[row * VLD + pos + 8] = hi2;
;     }
;     __syncthreads();
;     if (PF && kt + 1 < nkt) FA_PREFETCH(kt + 1); else if (PF && has_next_item) FA_PREFETCH_NEXT();
;     int k0 = kt * 64;
;     if (CAUSAL && k0 > qw0 + 15) continue;
.LBB0_1784:
	s_mov_b32 s9, 0

; #define FA_PREFETCH(kt_) do { int k0_ = (kt_) * 64; \
;     _Pragma("unroll") for (int i = 0; i < KPT; ++i) kreg[i] = __builtin_amdgcn_raw_buffer_load_b128(rsK, kvo[i], k0_ * k_stride * 2, 0); \
;     _Pragma("unroll") for (int i = 0; i < VPT; ++i) vreg[i] = __builtin_amdgcn_raw_buffer_load_b128(rsV, vvo[i], k0_ * 2, 0); } while (0)
; #define FA_PREFETCH_NEXT() do { \
;     _Pragma("unroll") for (int i = 0; i < KPT; ++i) kreg[i] = __builtin_amdgcn_raw_buffer_load_b128(rsNK, kvo[i], 0, 0); \
;     _Pragma("unroll") for (int i = 0; i < VPT; ++i) vreg[i] = __builtin_amdgcn_raw_buffer_load_b128(rsNV, vvo[i], 0, 0); } while (0)
; template <int NC, int DQK, int DV, bool CAUSAL, bool PF> ...
;     ...
;   for (int kt = 0; kt < nkt; ++kt) {
;     if (!PF) FA_PREFETCH(kt);
;     u16* Kb = Ks + (kt & 1) * KBUF; u16* Vb = Vs + (kt & 1) * VBUF;
;     _Pragma("unroll") for (int i = 0; i < KPT; ++i) { int id = tid + i * 512, row = id / KCH, cc = id % KCH; *(u32x4*)&Kb[row * KLD + cc * 8] = kreg[i]; }
;     _Pragma("unroll") for (int i = 0; i < VPT; ++i) {
;       int id = tid + i * 512, row = id >> 3, cc = id & 7;
;       int pos = 32 * (cc >> 2) + 16 * (cc & 1) + 4 * ((cc >> 1) & 1);
;       uint2 lo2, hi2; lo2.x = vreg[i][0]; lo2.y = vreg[i][1]; hi2.x = vreg[i][2]; hi2.y = vreg[i][3];
;       *(uint2*)&Vb[row * VLD + pos] = lo2; *(uint2*)&Vb[row * VLD + pos + 8] = hi2;
;     }
;     __syncthreads();
;     if (PF && kt + 1 < nkt) FA_PREFETCH(kt + 1); else if (PF && has_next_item) FA_PREFETCH_NEXT();
;     int k0 = kt * 64;
;     if (CAUSAL && k0 > qw0 + 15) continue;
.LBB0_1785:
	s_and_b32 s0, s34, 1
	s_mul_i32 s1, s0, 0x4400
	s_add_i32 s38, s1, 0
	s_mul_hi_u32 s0, s34, 0xaaaaaaab
	s_lshr_b32 s0, s0, 1
	s_mul_i32 s0, s0, 3
	s_sub_i32 s0, s34, s0
	s_mul_i32 s0, s0, 0x5000
	s_mov_b32 s37, s0
	s_mov_b32 s14, s78
	s_mov_b32 s15, s79
	s_cmp_lg_u32 s9, 0
	s_cbranch_scc1 .Lda_top_flag
	v_add3_u32 v0, s38, v210, v204
	s_waitcnt vmcnt(3)
	ds_write_b128 v0, v[34:37]
	v_add3_u32 v0, s38, v209, v205
	s_waitcnt vmcnt(2)
	ds_write_b128 v0, v[38:41]
	v_lshl_add_u32 v0, v206, 1, s37
	v_add3_u32 v0, v0, v211, v212
	v_add_u32_e32 v1, v0, v208
	v_add_u32_e32 v0, v0, v207
	v_add_u32_e32 v1, 0x8800, v1
	v_add_u32_e32 v0, 0x8800, v0
	s_waitcnt vmcnt(0)
	ds_write2_b64 v1, v[42:43], v[44:45] offset1:2
	s_waitcnt vmcnt(0)
	ds_write2_b64 v0, v[46:47], v[48:49] offset1:2
	s_waitcnt lgkmcnt(0)
	s_barrier
	buffer_load_dwordx4 v[34:37], v198, s[76:79], s36 offen
	buffer_load_dwordx4 v[38:41], v199, s[76:79], s36 offen
	buffer_load_dwordx4 v[46:49], v200, s[12:15], s31 offen
	buffer_load_dwordx4 v[42:45], v201, s[12:15], s31 offen
.Lda_top_join:
	s_sub_i32 s0, s35, 63
	v_cmp_le_i32_e32 vcc, s0, v203
	s_and_saveexec_b64 s[0:1], vcc
	s_cbranch_execz .LBB0_1784
	v_readlane_b32 s6, v254, 39
	v_cmp_gt_i32_e32 vcc, s35, v202
	s_nop 0
	v_mov_b32_e32 v0, s6
	ds_read_b32 v170, v0
	v_cmp_le_i32_e64 s[6:7], s35, v202
	s_cbranch_vccz .Lda_fast_sel
	s_cmp_lt_u32 s97, 0x100
	s_cbranch_scc1 .Lda_gen_cont
	s_cmp_eq_u32 s34, 0
	s_cbranch_scc1 .Lda_gen_cont
	s_sub_i32 s8, s35, 64
	v_cmp_le_i32_e32 vcc, s8, v202
	s_cbranch_vccnz .Ldb_flushB
	v_cmp_gt_i32_e32 vcc, s35, v202

; __device__ __forceinline__ uint2 pack4(float a, float b, float c, float d) { uint2 r; r.x = pk2(a, b); r.y = pk2(c, d); return r; }
; #define FA_PREFETCH_NEXT() do { \
;     _Pragma("unroll") for (int i = 0; i < KPT; ++i) kreg[i] = __builtin_amdgcn_raw_buffer_load_b128(rsNK, kvo[i], 0, 0); \
;     _Pragma("unroll") for (int i = 0; i < VPT; ++i) vreg[i] = __builtin_amdgcn_raw_buffer_load_b128(rsNV, vvo[i], 0, 0); } while (0)
; template <int NC, int DQK, int DV, bool CAUSAL, bool PF> ...
;     ...
;     _Pragma("unroll") for (int i = 0; i < KPT; ++i) { int id = tid + i * 512, row = id / KCH, cc = id % KCH; *(u32x4*)&Kb[row * KLD + cc * 8] = kreg[i]; }
;     _Pragma("unroll") for (int i = 0; i < VPT; ++i) {
;       int id = tid + i * 512, row = id >> 3, cc = id & 7;
;       int pos = 32 * (cc >> 2) + 16 * (cc & 1) + 4 * ((cc >> 1) & 1);
;       uint2 lo2, hi2; lo2.x = vreg[i][0]; lo2.y = vreg[i][1]; hi2.x = vreg[i][2]; hi2.y = vreg[i][3];
;       *(uint2*)&Vb[row * VLD + pos] = lo2; *(uint2*)&Vb[row * VLD + pos + 8] = hi2;
;     }
;     __syncthreads();
;     if (PF && kt + 1 < nkt) FA_PREFETCH(kt + 1); else if (PF && has_next_item) FA_PREFETCH_NEXT();
;     ...
;         _Pragma("unroll") for (int m = 0; m < 4; ++m) _Pragma("unroll") for (int j = 0; j < 4; ++j) { float pv = __builtin_amdgcn_exp2f(s[m][j] - mm); s[m][j] = pv; psum += pv; }
;       } else {
;         float cc = bb - mrun[c];
;         _Pragma("unroll") for (int m = 0; m < 4; ++m) _Pragma("unroll") for (int j = 0; j < 4; ++j) { float pv = __builtin_amdgcn_exp2f(s[m][j] * scale_log2 + cc); s[m][j] = pv; psum += pv; }
;       }
;       lsum[c] += psum;
;       _Pragma("unroll") for (int k2 = 0; k2 < 2; ++k2) {
;         uint2 lo = pack4(s[2 * k2][0], s[2 * k2][1], s[2 * k2][2], s[2 * k2][3]);
;         uint2 hi = pack4(s[2 * k2 + 1][0], s[2 * k2 + 1][1], s[2 * k2 + 1][2], s[2 * k2 + 1][3]);
;         uint4 pk; pk.x = lo.x; pk.y = lo.y; pk.z = hi.x; pk.w = hi.y;
;         pf[c][k2] = *(bf16x8*)&pk;
;       }
;     }
;     _Pragma("unroll") for (int k2 = 0; k2 < 2; ++k2) _Pragma("unroll") for (int v = 0; v < NVT; ++v) {
;       bf16x8 a = *(const bf16x8*)&Vb[(16 * v + fr) * VLD + 32 * k2 + fq * 8];
;       _Pragma("unroll") for (int c = 0; c < NC; ++c) O[c][v] = __builtin_amdgcn_mfma_f32_16x16x32_bf16(a, pf[c][k2], O[c][v], 0, 0, 0);
;       if ((v & 3) == 3) __builtin_amdgcn_sched_barrier(0);
;     }
.Lda_resc1_ret:
	v_sub_f32_e32 v175, v170, v171
	v_fmamk_f32 v0, v0, 0x3e38aa3b, v175
	v_fmamk_f32 v1, v1, 0x3e38aa3b, v175
	v_fmamk_f32 v2, v2, 0x3e38aa3b, v175
	v_fmamk_f32 v3, v3, 0x3e38aa3b, v175
	v_fmamk_f32 v4, v4, 0x3e38aa3b, v175
	v_fmamk_f32 v5, v5, 0x3e38aa3b, v175
	v_fmamk_f32 v6, v6, 0x3e38aa3b, v175
	v_fmamk_f32 v7, v7, 0x3e38aa3b, v175
	v_fmamk_f32 v8, v8, 0x3e38aa3b, v175
	v_fmamk_f32 v9, v9, 0x3e38aa3b, v175
	v_fmamk_f32 v10, v10, 0x3e38aa3b, v175
	v_fmamk_f32 v11, v11, 0x3e38aa3b, v175
	v_fmamk_f32 v12, v12, 0x3e38aa3b, v175
	v_fmamk_f32 v13, v13, 0x3e38aa3b, v175
	v_fmamk_f32 v14, v14, 0x3e38aa3b, v175
	v_fmamk_f32 v15, v15, 0x3e38aa3b, v175
	v_exp_f32_e32 v0, v0
	v_exp_f32_e32 v1, v1
	v_exp_f32_e32 v2, v2
	v_add_f32_e32 v174, v1, v0
	v_exp_f32_e32 v3, v3
	v_add_f32_e32 v174, v2, v174
	v_exp_f32_e32 v4, v4
	v_add_f32_e32 v174, v3, v174
	v_exp_f32_e32 v5, v5
	v_add_f32_e32 v174, v4, v174
	v_exp_f32_e32 v6, v6
	v_add_f32_e32 v174, v5, v174
	v_exp_f32_e32 v7, v7
	v_add_f32_e32 v174, v6, v174
	v_exp_f32_e32 v8, v8
	v_add_f32_e32 v174, v7, v174
	v_exp_f32_e32 v9, v9
	v_add_f32_e32 v174, v8, v174
	v_exp_f32_e32 v10, v10
	v_add_f32_e32 v174, v9, v174
	v_exp_f32_e32 v11, v11
	v_add_f32_e32 v174, v10, v174
	v_exp_f32_e32 v12, v12
	v_add_f32_e32 v174, v11, v174
	v_exp_f32_e32 v13, v13
	v_add_f32_e32 v174, v12, v174
	v_exp_f32_e32 v14, v14
	v_add_f32_e32 v174, v13, v174
	v_exp_f32_e32 v15, v15
	v_add_f32_e32 v174, v14, v174
	v_cvt_pk_bf16_f32 v0, v0, v1
	v_add_f32_e32 v174, v15, v174
	v_cvt_pk_bf16_f32 v1, v2, v3
	v_add_f32_e32 v191, v191, v174
	v_cvt_pk_bf16_f32 v2, v4, v5
	v_cvt_pk_bf16_f32 v3, v6, v7
	v_cvt_pk_bf16_f32 v4, v8, v9
	v_cvt_pk_bf16_f32 v5, v10, v11
	v_cvt_pk_bf16_f32 v6, v12, v13
	v_cvt_pk_bf16_f32 v7, v14, v15
	s_waitcnt vmcnt(0)
	s_xor_b32 s8, s38, 0x4400
	v_add3_u32 v174, s8, v210, v204
	v_add3_u32 v175, s8, v209, v205
	ds_write_b128 v174, v[34:37]
	ds_write_b128 v175, v[38:41]
	s_add_i32 s8, s37, 0x5000
	s_cmp_eq_u32 s8, 0xf000
	s_cselect_b32 s8, 0, s8
	v_lshl_add_u32 v174, v206, 1, s8
	v_add3_u32 v174, v174, v211, v212
	v_add_u32_e32 v175, v174, v208
	v_add_u32_e32 v174, v174, v207
	v_add_u32_e32 v175, 0x8800, v175
	v_add_u32_e32 v174, 0x8800, v174
	ds_write2_b64 v175, v[42:43], v[44:45] offset1:2
	ds_write2_b64 v174, v[46:47], v[48:49] offset1:2
	s_waitcnt lgkmcnt(12)
	v_mfma_f32_16x16x32_bf16 v[106:109], v[122:125], v[146:149], v[106:109]
	v_mfma_f32_16x16x32_bf16 v[110:113], v[122:125], v[0:3], v[110:113]
	v_mfma_f32_16x16x32_bf16 v[98:101], v[126:129], v[146:149], v[98:101]
	v_mfma_f32_16x16x32_bf16 v[102:105], v[126:129], v[0:3], v[102:105]
	s_waitcnt lgkmcnt(10)
	v_mfma_f32_16x16x32_bf16 v[90:93], v[130:133], v[146:149], v[90:93]
	v_mfma_f32_16x16x32_bf16 v[94:97], v[130:133], v[0:3], v[94:97]
	v_mfma_f32_16x16x32_bf16 v[78:81], v[142:145], v[146:149], v[78:81]
	v_mfma_f32_16x16x32_bf16 v[74:77], v[142:145], v[0:3], v[74:77]
	ds_read_b128 v[8:11], v173 offset:40000
	ds_read_b128 v[12:15], v173 offset:42560
	ds_read_b128 v[122:125], v173 offset:45120
	ds_read_b128 v[126:129], v173 offset:47680
	s_waitcnt lgkmcnt(12)
	v_mfma_f32_16x16x32_bf16 v[62:65], v[16:19], v[146:149], v[62:65]
	v_mfma_f32_16x16x32_bf16 v[70:73], v[16:19], v[0:3], v[70:73]
	v_mfma_f32_16x16x32_bf16 v[50:53], v[20:23], v[146:149], v[50:53]
	v_mfma_f32_16x16x32_bf16 v[66:69], v[20:23], v[0:3], v[66:69]
	ds_read_b128 v[130:133], v173 offset:50240
	ds_read_b128 v[142:145], v173 offset:52800
	s_waitcnt lgkmcnt(12)
	v_mfma_f32_16x16x32_bf16 v[54:57], v[24:27], v[146:149], v[54:57]
	v_mfma_f32_16x16x32_bf16 v[58:61], v[24:27], v[0:3], v[58:61]
	v_mfma_f32_16x16x32_bf16 v[82:85], v[28:31], v[146:149], v[82:85]
	v_mfma_f32_16x16x32_bf16 v[86:89], v[28:31], v[0:3], v[86:89]
	s_waitcnt lgkmcnt(10)
	v_mfma_f32_16x16x32_bf16 v[106:109], v[154:157], v[150:153], v[106:109]
	v_mfma_f32_16x16x32_bf16 v[110:113], v[154:157], v[4:7], v[110:113]
	v_mfma_f32_16x16x32_bf16 v[98:101], v[158:161], v[150:153], v[98:101]
	v_mfma_f32_16x16x32_bf16 v[102:105], v[158:161], v[4:7], v[102:105]
	s_waitcnt lgkmcnt(4)
	v_mfma_f32_16x16x32_bf16 v[90:93], v[8:11], v[150:153], v[90:93]
	v_mfma_f32_16x16x32_bf16 v[94:97], v[8:11], v[4:7], v[94:97]
	v_mfma_f32_16x16x32_bf16 v[78:81], v[12:15], v[150:153], v[78:81]
	v_mfma_f32_16x16x32_bf16 v[74:77], v[12:15], v[4:7], v[74:77]
	s_waitcnt lgkmcnt(2)
	v_mfma_f32_16x16x32_bf16 v[62:65], v[122:125], v[150:153], v[62:65]
	v_mfma_f32_16x16x32_bf16 v[70:73], v[122:125], v[4:7], v[70:73]
	v_mfma_f32_16x16x32_bf16 v[50:53], v[126:129], v[150:153], v[50:53]
	v_mfma_f32_16x16x32_bf16 v[66:69], v[126:129], v[4:7], v[66:69]
	s_waitcnt lgkmcnt(0)
	v_mfma_f32_16x16x32_bf16 v[54:57], v[130:133], v[150:153], v[54:57]
	v_mfma_f32_16x16x32_bf16 v[58:61], v[130:133], v[4:7], v[58:61]
	v_mfma_f32_16x16x32_bf16 v[82:85], v[142:145], v[150:153], v[82:85]
	v_mfma_f32_16x16x32_bf16 v[86:89], v[142:145], v[4:7], v[86:89]
	s_add_i32 s8, s36, 0x20000
	buffer_load_dwordx4 v[34:37], v198, s[76:79], s8 offen
	buffer_load_dwordx4 v[38:41], v199, s[76:79], s8 offen
	s_add_i32 s8, s31, 0x80
	buffer_load_dwordx4 v[46:49], v200, s[12:15], s8 offen
	buffer_load_dwordx4 v[42:45], v201, s[12:15], s8 offen
	s_mov_b32 s9, 1
	s_branch .Lda_1784b

; template <int NC, int DQK, int DV, bool CAUSAL, bool PF> ...
;     ...
;     _Pragma("unroll") for (int i = 0; i < KPT; ++i) { int id = tid + i * 512, row = id / KCH, cc = id % KCH; *(u32x4*)&Kb[row * KLD + cc * 8] = kreg[i]; }
;     _Pragma("unroll") for (int i = 0; i < VPT; ++i) {
;       int id = tid + i * 512, row = id >> 3, cc = id & 7;
;       int pos = 32 * (cc >> 2) + 16 * (cc & 1) + 4 * ((cc >> 1) & 1);
;       uint2 lo2, hi2; lo2.x = vreg[i][0]; lo2.y = vreg[i][1]; hi2.x = vreg[i][2]; hi2.y = vreg[i][3];
;       *(uint2*)&Vb[row * VLD + pos] = lo2; *(uint2*)&Vb[row * VLD + pos + 8] = hi2;
;     }
;     ...
;     _Pragma("unroll") for (int k2 = 0; k2 < 2; ++k2) _Pragma("unroll") for (int v = 0; v < NVT; ++v) {
;       bf16x8 a = *(const bf16x8*)&Vb[(16 * v + fr) * VLD + 32 * k2 + fq * 8];
;       _Pragma("unroll") for (int c = 0; c < NC; ++c) O[c][v] = __builtin_amdgcn_mfma_f32_16x16x32_bf16(a, pf[c][k2], O[c][v], 0, 0, 0);
;       if ((v & 3) == 3) __builtin_amdgcn_sched_barrier(0);
;     }
.Ldb_fastB:
	v_add3_u32 v172, s38, v32, v195
	s_cmp_eq_u32 s34, 0
	s_cbranch_scc1 .Ldb_B_nopend
	s_sub_i32 s8, s37, 0x5000
	s_cmp_lt_i32 s8, 0
	s_cselect_b32 s8, 0xa000, s8
	v_add3_u32 v173, s8, v32, v193
	s_waitcnt vmcnt(0)
	s_xor_b32 s8, s38, 0x4400
	v_add3_u32 v174, s8, v210, v204
	v_add3_u32 v175, s8, v209, v205
	ds_write_b128 v174, v[34:37]
	ds_write_b128 v175, v[38:41]
	s_add_i32 s8, s37, 0x5000
	s_cmp_eq_u32 s8, 0xf000
	s_cselect_b32 s8, 0, s8
	v_lshl_add_u32 v174, v206, 1, s8
	v_add3_u32 v174, v174, v211, v212
	v_add_u32_e32 v175, v174, v208
	v_add_u32_e32 v174, v174, v207
	v_add_u32_e32 v175, 0x8800, v175
	v_add_u32_e32 v174, 0x8800, v174
	ds_write2_b64 v175, v[42:43], v[44:45] offset1:2
	ds_write2_b64 v174, v[46:47], v[48:49] offset1:2
	ds_read_b128 v[0:3], v173 offset:34816
	ds_read_b128 v[4:7], v173 offset:37376
	ds_read_b128 v[8:11], v173 offset:39936
	ds_read_b128 v[12:15], v173 offset:42496
	ds_read_b128 v[16:19], v173 offset:45056
	ds_read_b128 v[20:23], v173 offset:47616
	ds_read_b128 v[24:27], v173 offset:50176
	ds_read_b128 v[28:31], v173 offset:52736
	s_waitcnt lgkmcnt(6)
	v_mfma_f32_16x16x32_bf16 v[106:109], v[0:3], v[146:149], v[106:109]
	v_mfma_f32_16x16x32_bf16 v[110:113], v[0:3], v[154:157], v[110:113]
	v_mfma_f32_16x16x32_bf16 v[98:101], v[4:7], v[146:149], v[98:101]
	v_mfma_f32_16x16x32_bf16 v[102:105], v[4:7], v[154:157], v[102:105]
	ds_read_b128 v[122:125], v173 offset:34880
	ds_read_b128 v[126:129], v173 offset:37440
	s_waitcnt lgkmcnt(6)
	v_mfma_f32_16x16x32_bf16 v[90:93], v[8:11], v[146:149], v[90:93]
	v_mfma_f32_16x16x32_bf16 v[94:97], v[8:11], v[154:157], v[94:97]
	v_mfma_f32_16x16x32_bf16 v[78:81], v[12:15], v[146:149], v[78:81]
	v_mfma_f32_16x16x32_bf16 v[74:77], v[12:15], v[154:157], v[74:77]
	ds_read_b128 v[130:133], v173 offset:40000
	ds_read_b128 v[142:145], v173 offset:42560
	ds_read_b128 v[0:3], v173 offset:45120
	ds_read_b128 v[4:7], v173 offset:47680
	s_waitcnt lgkmcnt(8)
	v_mfma_f32_16x16x32_bf16 v[62:65], v[16:19], v[146:149], v[62:65]
	v_mfma_f32_16x16x32_bf16 v[70:73], v[16:19], v[154:157], v[70:73]
	v_mfma_f32_16x16x32_bf16 v[50:53], v[20:23], v[146:149], v[50:53]
	v_mfma_f32_16x16x32_bf16 v[66:69], v[20:23], v[154:157], v[66:69]
	ds_read_b128 v[8:11], v173 offset:50240
	ds_read_b128 v[12:15], v173 offset:52800
	s_waitcnt lgkmcnt(8)
	v_mfma_f32_16x16x32_bf16 v[54:57], v[24:27], v[146:149], v[54:57]
	v_mfma_f32_16x16x32_bf16 v[58:61], v[24:27], v[154:157], v[58:61]
	v_mfma_f32_16x16x32_bf16 v[82:85], v[28:31], v[146:149], v[82:85]
	v_mfma_f32_16x16x32_bf16 v[86:89], v[28:31], v[154:157], v[86:89]
	ds_read_b128 v[16:19], v172 offset:64
	ds_read_b128 v[20:23], v172 offset:4416
	ds_read_b128 v[24:27], v172 offset:8768
	ds_read_b128 v[28:31], v172 offset:13120
	s_waitcnt lgkmcnt(10)
	v_mfma_f32_16x16x32_bf16 v[106:109], v[122:125], v[150:153], v[106:109]
	v_mfma_f32_16x16x32_bf16 v[110:113], v[122:125], v[158:161], v[110:113]
	v_mfma_f32_16x16x32_bf16 v[98:101], v[126:129], v[150:153], v[98:101]
	v_mfma_f32_16x16x32_bf16 v[102:105], v[126:129], v[158:161], v[102:105]
	s_waitcnt lgkmcnt(8)
	v_mfma_f32_16x16x32_bf16 v[90:93], v[130:133], v[150:153], v[90:93]
	v_mfma_f32_16x16x32_bf16 v[94:97], v[130:133], v[158:161], v[94:97]
	v_mfma_f32_16x16x32_bf16 v[78:81], v[142:145], v[150:153], v[78:81]
	v_mfma_f32_16x16x32_bf16 v[74:77], v[142:145], v[158:161], v[74:77]
	ds_read_b128 v[122:125], v172
	ds_read_b128 v[126:129], v172 offset:4352
	ds_read_b128 v[130:133], v172 offset:8704
	ds_read_b128 v[142:145], v172 offset:13056
	s_waitcnt lgkmcnt(10)
	v_mfma_f32_16x16x32_bf16 v[62:65], v[0:3], v[150:153], v[62:65]
	v_mfma_f32_16x16x32_bf16 v[70:73], v[0:3], v[158:161], v[70:73]
	v_mfma_f32_16x16x32_bf16 v[50:53], v[4:7], v[150:153], v[50:53]
	v_mfma_f32_16x16x32_bf16 v[66:69], v[4:7], v[158:161], v[66:69]
	s_waitcnt lgkmcnt(8)
	v_mfma_f32_16x16x32_bf16 v[54:57], v[8:11], v[150:153], v[54:57]
	v_mfma_f32_16x16x32_bf16 v[58:61], v[8:11], v[158:161], v[58:61]
	v_mfma_f32_16x16x32_bf16 v[82:85], v[12:15], v[150:153], v[82:85]
	v_mfma_f32_16x16x32_bf16 v[86:89], v[12:15], v[158:161], v[86:89]
	ds_read_b128 v[0:3], v172 offset:128
	ds_read_b128 v[4:7], v172 offset:4480
	ds_read_b128 v[8:11], v172 offset:8832
	ds_read_b128 v[12:15], v172 offset:13184
	s_branch .Ldb_B_qk
.Ldb_B_nopend:
	s_waitcnt vmcnt(0)
	s_xor_b32 s8, s38, 0x4400
	v_add3_u32 v174, s8, v210, v204
	v_add3_u32 v175, s8, v209, v205
	ds_write_b128 v174, v[34:37]
	ds_write_b128 v175, v[38:41]
	s_add_i32 s8, s37, 0x5000
	s_cmp_eq_u32 s8, 0xf000
	s_cselect_b32 s8, 0, s8
	v_lshl_add_u32 v174, v206, 1, s8
	v_add3_u32 v174, v174, v211, v212
	v_add_u32_e32 v175, v174, v208
	v_add_u32_e32 v174, v174, v207
	v_add_u32_e32 v175, 0x8800, v175
	v_add_u32_e32 v174, 0x8800, v174
	ds_write2_b64 v175, v[42:43], v[44:45] offset1:2
	ds_write2_b64 v174, v[46:47], v[48:49] offset1:2
	s_waitcnt lgkmcnt(0)
	ds_read_b128 v[16:19], v172 offset:64
	ds_read_b128 v[20:23], v172 offset:4416
	ds_read_b128 v[24:27], v172 offset:8768
	ds_read_b128 v[28:31], v172 offset:13120
	ds_read_b128 v[122:125], v172
	ds_read_b128 v[126:129], v172 offset:4352
	ds_read_b128 v[130:133], v172 offset:8704
	ds_read_b128 v[142:145], v172 offset:13056
	ds_read_b128 v[0:3], v172 offset:128
	ds_read_b128 v[4:7], v172 offset:4480
	ds_read_b128 v[8:11], v172 offset:8832
	ds_read_b128 v[12:15], v172 offset:13184

; __device__ __forceinline__ uint2 pack4(float a, float b, float c, float d) { uint2 r; r.x = pk2(a, b); r.y = pk2(c, d); return r; }
; #define FA_PREFETCH(kt_) do { int k0_ = (kt_) * 64; \
;     _Pragma("unroll") for (int i = 0; i < KPT; ++i) kreg[i] = __builtin_amdgcn_raw_buffer_load_b128(rsK, kvo[i], k0_ * k_stride * 2, 0); \
;     _Pragma("unroll") for (int i = 0; i < VPT; ++i) vreg[i] = __builtin_amdgcn_raw_buffer_load_b128(rsV, vvo[i], k0_ * 2, 0); } while (0)
; #define FA_PREFETCH_NEXT() do { \
;     _Pragma("unroll") for (int i = 0; i < KPT; ++i) kreg[i] = __builtin_amdgcn_raw_buffer_load_b128(rsNK, kvo[i], 0, 0); \
;     _Pragma("unroll") for (int i = 0; i < VPT; ++i) vreg[i] = __builtin_amdgcn_raw_buffer_load_b128(rsNV, vvo[i], 0, 0); } while (0)
; template <int NC, int DQK, int DV, bool CAUSAL, bool PF> ...
;     ...
;     if (PF && kt + 1 < nkt) FA_PREFETCH(kt + 1); else if (PF && has_next_item) FA_PREFETCH_NEXT();
;     ...
;         _Pragma("unroll") for (int m = 0; m < 4; ++m) _Pragma("unroll") for (int j = 0; j < 4; ++j) { float pv = __builtin_amdgcn_exp2f(s[m][j] - mm); s[m][j] = pv; psum += pv; }
;       } else {
;         float cc = bb - mrun[c];
;         _Pragma("unroll") for (int m = 0; m < 4; ++m) _Pragma("unroll") for (int j = 0; j < 4; ++j) { float pv = __builtin_amdgcn_exp2f(s[m][j] * scale_log2 + cc); s[m][j] = pv; psum += pv; }
;       }
;       lsum[c] += psum;
;       _Pragma("unroll") for (int k2 = 0; k2 < 2; ++k2) {
;         uint2 lo = pack4(s[2 * k2][0], s[2 * k2][1], s[2 * k2][2], s[2 * k2][3]);
;         uint2 hi = pack4(s[2 * k2 + 1][0], s[2 * k2 + 1][1], s[2 * k2 + 1][2], s[2 * k2 + 1][3]);
;         uint4 pk; pk.x = lo.x; pk.y = lo.y; pk.z = hi.x; pk.w = hi.y;
;         pf[c][k2] = *(bf16x8*)&pk;
;       }
.Ldb_resc1_ret:
	v_sub_f32_e32 v175, v170, v171
	v_fmamk_f32 v0, v0, 0x3e38aa3b, v175
	v_fmamk_f32 v1, v1, 0x3e38aa3b, v175
	v_fmamk_f32 v2, v2, 0x3e38aa3b, v175
	v_fmamk_f32 v3, v3, 0x3e38aa3b, v175
	v_fmamk_f32 v4, v4, 0x3e38aa3b, v175
	v_fmamk_f32 v5, v5, 0x3e38aa3b, v175
	v_fmamk_f32 v6, v6, 0x3e38aa3b, v175
	v_fmamk_f32 v7, v7, 0x3e38aa3b, v175
	v_fmamk_f32 v8, v8, 0x3e38aa3b, v175
	v_fmamk_f32 v9, v9, 0x3e38aa3b, v175
	v_fmamk_f32 v10, v10, 0x3e38aa3b, v175
	v_fmamk_f32 v11, v11, 0x3e38aa3b, v175
	v_fmamk_f32 v12, v12, 0x3e38aa3b, v175
	v_fmamk_f32 v13, v13, 0x3e38aa3b, v175
	v_fmamk_f32 v14, v14, 0x3e38aa3b, v175
	v_fmamk_f32 v15, v15, 0x3e38aa3b, v175
	v_exp_f32_e32 v0, v0
	v_exp_f32_e32 v1, v1
	v_exp_f32_e32 v2, v2
	v_add_f32_e32 v174, v1, v0
	v_exp_f32_e32 v3, v3
	v_add_f32_e32 v174, v2, v174
	v_exp_f32_e32 v4, v4
	v_add_f32_e32 v174, v3, v174
	v_exp_f32_e32 v5, v5
	v_add_f32_e32 v174, v4, v174
	v_exp_f32_e32 v6, v6
	v_add_f32_e32 v174, v5, v174
	v_exp_f32_e32 v7, v7
	v_add_f32_e32 v174, v6, v174
	v_exp_f32_e32 v8, v8
	v_add_f32_e32 v174, v7, v174
	v_exp_f32_e32 v9, v9
	v_add_f32_e32 v174, v8, v174
	v_exp_f32_e32 v10, v10
	v_add_f32_e32 v174, v9, v174
	v_exp_f32_e32 v11, v11
	v_add_f32_e32 v174, v10, v174
	v_exp_f32_e32 v12, v12
	v_add_f32_e32 v174, v11, v174
	v_exp_f32_e32 v13, v13
	v_add_f32_e32 v174, v12, v174
	v_exp_f32_e32 v14, v14
	v_add_f32_e32 v174, v13, v174
	v_exp_f32_e32 v15, v15
	v_add_f32_e32 v174, v14, v174
	v_cvt_pk_bf16_f32 v154, v0, v1
	v_add_f32_e32 v174, v15, v174
	v_cvt_pk_bf16_f32 v155, v2, v3
	v_add_f32_e32 v191, v191, v174
	v_cvt_pk_bf16_f32 v156, v4, v5
	v_cvt_pk_bf16_f32 v157, v6, v7
	v_cvt_pk_bf16_f32 v158, v8, v9
	v_cvt_pk_bf16_f32 v159, v10, v11
	v_cvt_pk_bf16_f32 v160, v12, v13
	v_cvt_pk_bf16_f32 v161, v14, v15
	s_add_i32 s8, s36, 0x20000
	buffer_load_dwordx4 v[34:37], v198, s[76:79], s8 offen
	buffer_load_dwordx4 v[38:41], v199, s[76:79], s8 offen
	s_add_i32 s8, s31, 0x80
	buffer_load_dwordx4 v[46:49], v200, s[12:15], s8 offen
	buffer_load_dwordx4 v[42:45], v201, s[12:15], s8 offen
	s_mov_b32 s9, 1
	s_branch .Lda_1784b

; template <int NC, int DQK, int DV, bool CAUSAL, bool PF> ...
;     ...
;     __syncthreads();
;     ...
;     _Pragma("unroll") for (int k2 = 0; k2 < 2; ++k2) _Pragma("unroll") for (int v = 0; v < NVT; ++v) {
;       bf16x8 a = *(const bf16x8*)&Vb[(16 * v + fr) * VLD + 32 * k2 + fq * 8];
;       _Pragma("unroll") for (int c = 0; c < NC; ++c) O[c][v] = __builtin_amdgcn_mfma_f32_16x16x32_bf16(a, pf[c][k2], O[c][v], 0, 0, 0);
;       if ((v & 3) == 3) __builtin_amdgcn_sched_barrier(0);
;     }
.Ldb_flushB:
	s_sub_i32 s8, s37, 0x5000
	s_cmp_lt_i32 s8, 0
	s_cselect_b32 s8, 0xa000, s8
	v_add3_u32 v173, s8, v32, v193
	ds_read_b128 v[0:3], v173 offset:34816
	ds_read_b128 v[4:7], v173 offset:37376
	ds_read_b128 v[8:11], v173 offset:39936
	ds_read_b128 v[12:15], v173 offset:42496
	ds_read_b128 v[16:19], v173 offset:45056
	ds_read_b128 v[20:23], v173 offset:47616
	ds_read_b128 v[24:27], v173 offset:50176
	ds_read_b128 v[28:31], v173 offset:52736
	s_waitcnt lgkmcnt(6)
	v_mfma_f32_16x16x32_bf16 v[106:109], v[0:3], v[146:149], v[106:109]
	v_mfma_f32_16x16x32_bf16 v[110:113], v[0:3], v[154:157], v[110:113]
	v_mfma_f32_16x16x32_bf16 v[98:101], v[4:7], v[146:149], v[98:101]
	v_mfma_f32_16x16x32_bf16 v[102:105], v[4:7], v[154:157], v[102:105]
	ds_read_b128 v[122:125], v173 offset:34880
	ds_read_b128 v[126:129], v173 offset:37440
	s_waitcnt lgkmcnt(6)
	v_mfma_f32_16x16x32_bf16 v[90:93], v[8:11], v[146:149], v[90:93]
	v_mfma_f32_16x16x32_bf16 v[94:97], v[8:11], v[154:157], v[94:97]
	v_mfma_f32_16x16x32_bf16 v[78:81], v[12:15], v[146:149], v[78:81]
	v_mfma_f32_16x16x32_bf16 v[74:77], v[12:15], v[154:157], v[74:77]
	ds_read_b128 v[130:133], v173 offset:40000
	ds_read_b128 v[142:145], v173 offset:42560
	ds_read_b128 v[0:3], v173 offset:45120
	ds_read_b128 v[4:7], v173 offset:47680
	s_waitcnt lgkmcnt(8)
	v_mfma_f32_16x16x32_bf16 v[62:65], v[16:19], v[146:149], v[62:65]
	v_mfma_f32_16x16x32_bf16 v[70:73], v[16:19], v[154:157], v[70:73]
	v_mfma_f32_16x16x32_bf16 v[50:53], v[20:23], v[146:149], v[50:53]
	v_mfma_f32_16x16x32_bf16 v[66:69], v[20:23], v[154:157], v[66:69]
	ds_read_b128 v[8:11], v173 offset:50240
	ds_read_b128 v[12:15], v173 offset:52800
	s_waitcnt lgkmcnt(8)
	v_mfma_f32_16x16x32_bf16 v[54:57], v[24:27], v[146:149], v[54:57]
	v_mfma_f32_16x16x32_bf16 v[58:61], v[24:27], v[154:157], v[58:61]
	v_mfma_f32_16x16x32_bf16 v[82:85], v[28:31], v[146:149], v[82:85]
	v_mfma_f32_16x16x32_bf16 v[86:89], v[28:31], v[154:157], v[86:89]
	s_waitcnt lgkmcnt(6)
	v_mfma_f32_16x16x32_bf16 v[106:109], v[122:125], v[150:153], v[106:109]
	v_mfma_f32_16x16x32_bf16 v[110:113], v[122:125], v[158:161], v[110:113]
	v_mfma_f32_16x16x32_bf16 v[98:101], v[126:129], v[150:153], v[98:101]
	v_mfma_f32_16x16x32_bf16 v[102:105], v[126:129], v[158:161], v[102:105]
	s_waitcnt lgkmcnt(4)
	v_mfma_f32_16x16x32_bf16 v[90:93], v[130:133], v[150:153], v[90:93]
	v_mfma_f32_16x16x32_bf16 v[94:97], v[130:133], v[158:161], v[94:97]
	v_mfma_f32_16x16x32_bf16 v[78:81], v[142:145], v[150:153], v[78:81]
	v_mfma_f32_16x16x32_bf16 v[74:77], v[142:145], v[158:161], v[74:77]
	s_waitcnt lgkmcnt(2)
	v_mfma_f32_16x16x32_bf16 v[62:65], v[0:3], v[150:153], v[62:65]
	v_mfma_f32_16x16x32_bf16 v[70:73], v[0:3], v[158:161], v[70:73]
	v_mfma_f32_16x16x32_bf16 v[50:53], v[4:7], v[150:153], v[50:53]
	v_mfma_f32_16x16x32_bf16 v[66:69], v[4:7], v[158:161], v[66:69]
	s_waitcnt lgkmcnt(0)
	v_mfma_f32_16x16x32_bf16 v[54:57], v[8:11], v[150:153], v[54:57]
	v_mfma_f32_16x16x32_bf16 v[58:61], v[8:11], v[158:161], v[58:61]
	v_mfma_f32_16x16x32_bf16 v[82:85], v[12:15], v[150:153], v[82:85]
	v_mfma_f32_16x16x32_bf16 v[86:89], v[12:15], v[158:161], v[86:89]
	v_cmp_gt_i32_e32 vcc, s35, v202
	s_branch .Lda_gen_cont
.Lda_top_flag:
	s_waitcnt lgkmcnt(0)
	s_barrier
	s_branch .Lda_top_join
